# GEMM K-loop header aligned to a 64-byte instruction-cache line (s_nop fill)
# baseline (speedup 1.0000x reference)
.LBB0_234:
	s_add_u32 s40, s40, 0x80
	s_addc_u32 s41, s41, 0
	s_add_u32 s39, s42, 0x100
	v_mov_b32_e32 v0, 0
	s_addc_u32 s78, s43, 0
	s_mov_b32 s42, 0
	v_mov_b32_e32 v1, v0
	v_mov_b32_e32 v2, v0
	v_mov_b32_e32 v3, v0
	v_mov_b32_e32 v32, v0
	v_mov_b32_e32 v33, v0
	v_mov_b32_e32 v34, v0
	v_mov_b32_e32 v35, v0
	v_mov_b32_e32 v4, v0
	v_mov_b32_e32 v5, v0
	v_mov_b32_e32 v6, v0
	v_mov_b32_e32 v7, v0
	v_mov_b32_e32 v36, v0
	v_mov_b32_e32 v37, v0
	v_mov_b32_e32 v38, v0
	v_mov_b32_e32 v39, v0
	v_mov_b32_e32 v8, v0
	v_mov_b32_e32 v9, v0
	v_mov_b32_e32 v10, v0
	v_mov_b32_e32 v11, v0
	v_mov_b32_e32 v40, v0
	v_mov_b32_e32 v41, v0
	v_mov_b32_e32 v42, v0
	v_mov_b32_e32 v43, v0
	v_mov_b32_e32 v12, v0
	v_mov_b32_e32 v13, v0
	v_mov_b32_e32 v14, v0
	v_mov_b32_e32 v15, v0
	v_mov_b32_e32 v44, v0
	v_mov_b32_e32 v45, v0
	v_mov_b32_e32 v46, v0
	v_mov_b32_e32 v47, v0
	v_mov_b32_e32 v64, v0
	v_mov_b32_e32 v65, v0
	v_mov_b32_e32 v66, v0
	v_mov_b32_e32 v67, v0
	v_mov_b32_e32 v96, v0
	v_mov_b32_e32 v97, v0
	v_mov_b32_e32 v98, v0
	v_mov_b32_e32 v99, v0
	v_mov_b32_e32 v68, v0
	v_mov_b32_e32 v69, v0
	v_mov_b32_e32 v70, v0
	v_mov_b32_e32 v71, v0
	v_mov_b32_e32 v100, v0
	v_mov_b32_e32 v101, v0
	v_mov_b32_e32 v102, v0
	v_mov_b32_e32 v103, v0
	v_mov_b32_e32 v72, v0
	v_mov_b32_e32 v73, v0
	v_mov_b32_e32 v74, v0
	v_mov_b32_e32 v75, v0
	v_mov_b32_e32 v104, v0
	v_mov_b32_e32 v105, v0
	v_mov_b32_e32 v106, v0
	v_mov_b32_e32 v107, v0
	v_mov_b32_e32 v76, v0
	v_mov_b32_e32 v77, v0
	v_mov_b32_e32 v78, v0
	v_mov_b32_e32 v79, v0
	v_mov_b32_e32 v108, v0
	v_mov_b32_e32 v109, v0
	v_mov_b32_e32 v110, v0
	v_mov_b32_e32 v111, v0
	v_mov_b32_e32 v16, v0
	v_mov_b32_e32 v17, v0
	v_mov_b32_e32 v18, v0
	v_mov_b32_e32 v19, v0
	v_mov_b32_e32 v48, v0
	v_mov_b32_e32 v49, v0
	v_mov_b32_e32 v50, v0
	v_mov_b32_e32 v51, v0
	v_mov_b32_e32 v20, v0
	v_mov_b32_e32 v21, v0
	s_waitcnt lgkmcnt(0)
	v_mov_b32_e32 v22, v0
	v_mov_b32_e32 v23, v0
	v_mov_b32_e32 v52, v0
	v_mov_b32_e32 v53, v0
	v_mov_b32_e32 v54, v0
	v_mov_b32_e32 v55, v0
	v_mov_b32_e32 v24, v0
	v_mov_b32_e32 v25, v0
	v_mov_b32_e32 v26, v0
	v_mov_b32_e32 v27, v0
	v_mov_b32_e32 v56, v0
	v_mov_b32_e32 v57, v0
	v_mov_b32_e32 v58, v0
	v_mov_b32_e32 v59, v0
	v_mov_b32_e32 v28, v0
	v_mov_b32_e32 v29, v0
	v_mov_b32_e32 v30, v0
	v_mov_b32_e32 v31, v0
	v_mov_b32_e32 v60, v0
	v_mov_b32_e32 v61, v0
	v_mov_b32_e32 v62, v0
	v_mov_b32_e32 v63, v0
	v_mov_b32_e32 v80, v0
	v_mov_b32_e32 v81, v0
	v_mov_b32_e32 v82, v0
	v_mov_b32_e32 v83, v0
	v_mov_b32_e32 v112, v0
	v_mov_b32_e32 v113, v0
	v_mov_b32_e32 v114, v0
	v_mov_b32_e32 v115, v0
	v_mov_b32_e32 v84, v0
	v_mov_b32_e32 v85, v0
	v_mov_b32_e32 v86, v0
	v_mov_b32_e32 v87, v0
	v_mov_b32_e32 v116, v0
	v_mov_b32_e32 v117, v0
	v_mov_b32_e32 v118, v0
	v_mov_b32_e32 v119, v0
	v_mov_b32_e32 v88, v0
	v_mov_b32_e32 v89, v0
	v_mov_b32_e32 v90, v0
	v_mov_b32_e32 v91, v0
	v_mov_b32_e32 v120, v0
	v_mov_b32_e32 v121, v0
	v_mov_b32_e32 v122, v0
	v_mov_b32_e32 v123, v0
	v_mov_b32_e32 v92, v0
	v_mov_b32_e32 v93, v0
	v_mov_b32_e32 v94, v0
	v_mov_b32_e32 v95, v0
	v_mov_b32_e32 v124, v0
	v_mov_b32_e32 v125, v0
	v_mov_b32_e32 v126, v0
	v_mov_b32_e32 v127, v0
	.p2alignl 6, 3212836864
